# 4-slot ring k-loops: tile-2 LDS-DMA issued before the barrier-state save barrier
# speedup vs baseline: 1.0025x; 1.0022x over previous
.LBB0_52:
	s_ashr_i32 s0, s5, 31
	s_lshr_b32 s0, s0, 27
	s_add_i32 s0, s5, s0
	s_and_b32 s1, s0, 0xffffffe0
	s_sub_i32 s7, s5, s1
	s_lshl_b32 s0, s0, 2
	s_and_b32 s6, s0, 0xffffff80
	s_mul_i32 s0, s7, 0x84000
	s_ashr_i32 s1, s0, 31
	s_lshl_b64 s[0:1], s[0:1], 1
	v_lshl_add_u64 v[0:1], v[98:99], 0, s[0:1]
	v_readfirstlane_b32 s8, v142
	v_lshl_add_u64 v[4:5], v[0:1], 0, v[112:113]
	s_mov_b32 m0, s8
	v_readfirstlane_b32 s8, v143
	global_load_lds_dwordx4 v[4:5], off
	v_lshl_add_u64 v[6:7], v[0:1], 0, v[114:115]
	s_mov_b32 m0, s8
	v_readfirstlane_b32 s8, v144
	v_add_u32_e32 v10, 0x3000, v142
	v_mad_i64_i32 v[2:3], s[10:11], s6, v188, v[100:101]
	global_load_lds_dwordx4 v[6:7], off
	v_lshl_add_u64 v[0:1], v[0:1], 0, v[96:97]
	s_mov_b32 m0, s8
	v_readfirstlane_b32 s8, v10
	v_add_u32_e32 v10, 0x4000, v142
	global_load_lds_dwordx4 v[0:1], off
	v_lshl_add_u64 v[8:9], v[2:3], 0, v[112:113]
	s_mov_b32 m0, s8
	v_readfirstlane_b32 s8, v10
	v_add_u32_e32 v10, 0x5000, v142
	global_load_lds_dwordx4 v[8:9], off
	v_lshl_add_u64 v[2:3], v[2:3], 0, v[114:115]
	s_mov_b32 m0, s8
	v_readfirstlane_b32 s8, v10
	global_load_lds_dwordx4 v[2:3], off
	v_lshl_add_u64 v[4:5], v[4:5], 0, 64
	s_mov_b32 m0, s8
	v_lshl_add_u64 v[0:1], v[0:1], 0, 64
	global_load_lds_dwordx4 v[4:5], off
	v_lshl_add_u64 v[4:5], v[6:7], 0, 64
	v_add_u32_e32 v6, 0x6000, v142
	s_mov_b32 s9, 2
	v_readfirstlane_b32 s8, v6
	s_mov_b32 m0, s8
	v_mad_i64_i32 v[116:117], s[10:11], s6, v188, v[102:103]
	global_load_lds_dwordx4 v[4:5], off
	v_add_u32_e32 v4, 0x7000, v142
	v_mad_i64_i32 v[118:119], s[10:11], s6, v188, v[104:105]
	v_readfirstlane_b32 s8, v4
	v_add_u32_e32 v4, 0x8000, v142
	s_mov_b32 m0, s8
	v_readfirstlane_b32 s8, v4
	global_load_lds_dwordx4 v[0:1], off
	v_lshl_add_u64 v[0:1], v[8:9], 0, 64
	s_mov_b32 m0, s8
	v_lshl_add_u64 v[120:121], v[106:107], 0, s[0:1]
	global_load_lds_dwordx4 v[0:1], off
	v_lshl_add_u64 v[0:1], v[2:3], 0, 64
	v_add_u32_e32 v2, 0x9000, v142
	v_lshl_add_u64 v[122:123], v[108:109], 0, s[0:1]
	v_readfirstlane_b32 s8, v2
	s_mov_b32 m0, s8
	v_lshl_add_u64 v[124:125], v[110:111], 0, s[0:1]
	global_load_lds_dwordx4 v[0:1], off
	v_mov_b32_e32 v0, 0
	s_mov_b32 s8, 0
	s_mov_b64 s[0:1], 0
	v_mov_b32_e32 v1, v0
	v_mov_b32_e32 v2, v0
	v_mov_b32_e32 v3, v0
	v_mov_b32_e32 v12, v0
	v_mov_b32_e32 v13, v0
	v_mov_b32_e32 v14, v0
	v_mov_b32_e32 v15, v0
	v_mov_b32_e32 v4, v0
	v_mov_b32_e32 v5, v0
	v_mov_b32_e32 v6, v0
	v_mov_b32_e32 v7, v0
	v_mov_b32_e32 v8, v0
	v_mov_b32_e32 v9, v0
	v_mov_b32_e32 v10, v0
	v_mov_b32_e32 v11, v0
	v_mov_b32_e32 v16, v0
	v_mov_b32_e32 v17, v0
	v_mov_b32_e32 v18, v0
	v_mov_b32_e32 v19, v0
	v_mov_b32_e32 v20, v0
	v_mov_b32_e32 v21, v0
	v_mov_b32_e32 v22, v0
	v_mov_b32_e32 v23, v0
	v_mov_b32_e32 v24, v0
	v_mov_b32_e32 v25, v0
	v_mov_b32_e32 v26, v0
	v_mov_b32_e32 v27, v0
	v_mov_b32_e32 v28, v0
	v_mov_b32_e32 v29, v0
	v_mov_b32_e32 v30, v0
	v_mov_b32_e32 v31, v0
	v_mov_b32_e32 v32, v0
	v_mov_b32_e32 v33, v0
	v_mov_b32_e32 v34, v0
	v_mov_b32_e32 v35, v0
	v_mov_b32_e32 v36, v0
	v_mov_b32_e32 v37, v0
	v_mov_b32_e32 v38, v0
	v_mov_b32_e32 v39, v0
	v_mov_b32_e32 v40, v0
	v_mov_b32_e32 v41, v0
	v_mov_b32_e32 v42, v0
	v_mov_b32_e32 v43, v0
	v_mov_b32_e32 v44, v0
	v_mov_b32_e32 v45, v0
	v_mov_b32_e32 v46, v0
	v_mov_b32_e32 v47, v0
	v_mov_b32_e32 v48, v0
	v_mov_b32_e32 v49, v0
	v_mov_b32_e32 v50, v0
	v_mov_b32_e32 v51, v0
	v_mov_b32_e32 v52, v0
	v_mov_b32_e32 v53, v0
	v_mov_b32_e32 v54, v0
	v_mov_b32_e32 v55, v0
	v_mov_b32_e32 v56, v0
	v_mov_b32_e32 v57, v0
	v_mov_b32_e32 v58, v0
	v_mov_b32_e32 v59, v0
	v_mov_b32_e32 v60, v0
	v_mov_b32_e32 v61, v0
	v_mov_b32_e32 v62, v0
	v_mov_b32_e32 v63, v0
	v_mov_b32_e32 v64, v0
	v_mov_b32_e32 v65, v0
	v_mov_b32_e32 v66, v0
	v_mov_b32_e32 v67, v0
	v_mov_b32_e32 v68, v0
	v_mov_b32_e32 v69, v0
	v_mov_b32_e32 v70, v0
	v_mov_b32_e32 v71, v0
	v_mov_b32_e32 v72, v0
	v_mov_b32_e32 v73, v0
	v_mov_b32_e32 v74, v0
	v_mov_b32_e32 v75, v0
	v_mov_b32_e32 v76, v0
	v_mov_b32_e32 v77, v0
	v_mov_b32_e32 v78, v0
	v_mov_b32_e32 v79, v0
	v_mov_b32_e32 v80, v0
	v_mov_b32_e32 v81, v0
	v_mov_b32_e32 v82, v0
	v_mov_b32_e32 v83, v0
	v_mov_b32_e32 v84, v0
	v_mov_b32_e32 v85, v0
	v_mov_b32_e32 v86, v0
	v_mov_b32_e32 v87, v0
	v_mov_b32_e32 v88, v0
	v_mov_b32_e32 v89, v0
	v_mov_b32_e32 v90, v0
	v_mov_b32_e32 v91, v0
	v_mov_b32_e32 v92, v0
	v_mov_b32_e32 v93, v0
	v_mov_b32_e32 v94, v0
	v_mov_b32_e32 v95, v0
	v_readfirstlane_b32 s34, v142
	s_mov_b32 s36, 0x5000
	s_mov_b32 s37, 0xffff1000
	ds_read_b32 v252, v183
	ds_read_b32 v253, v184
	s_add_u32 s39, s34, 0xa000
	v_lshl_add_u64 v[126:127], v[124:125], 0, s[2:3]
	s_mov_b32 m0, s39
	s_nop 0
	global_load_lds_dwordx4 v[126:127], off
	v_lshl_add_u64 v[126:127], v[122:123], 0, s[2:3]
	s_add_u32 m0, s39, 0x1000
	s_nop 0
	global_load_lds_dwordx4 v[126:127], off
	v_lshl_add_u64 v[126:127], v[120:121], 0, s[2:3]
	s_add_u32 m0, s39, 0x2000
	s_nop 0
	global_load_lds_dwordx4 v[126:127], off
	v_lshl_add_u64 v[126:127], v[118:119], 0, s[2:3]
	s_add_u32 m0, s39, 0x3000
	s_nop 0
	global_load_lds_dwordx4 v[126:127], off
	v_lshl_add_u64 v[126:127], v[116:117], 0, s[2:3]
	s_add_u32 m0, s39, 0x4000
	s_nop 0
	global_load_lds_dwordx4 v[126:127], off
	s_waitcnt lgkmcnt(0)
	v_readfirstlane_b32 s46, v252
	v_readfirstlane_b32 s47, v253
	s_barrier
	s_add_u32 s39, s34, 0xf000
	v_lshl_add_u64 v[126:127], v[124:125], 0, s[30:31]
	s_mov_b32 m0, s39
	s_nop 0
	global_load_lds_dwordx4 v[126:127], off
	v_lshl_add_u64 v[126:127], v[122:123], 0, s[30:31]
	s_add_u32 m0, s39, 0x1000
	s_nop 0
	global_load_lds_dwordx4 v[126:127], off
	v_lshl_add_u64 v[126:127], v[120:121], 0, s[30:31]
	s_add_u32 m0, s39, 0x2000
	s_nop 0
	global_load_lds_dwordx4 v[126:127], off
	v_lshl_add_u64 v[126:127], v[118:119], 0, s[30:31]
	s_add_u32 m0, s39, 0x3000
	s_nop 0
	global_load_lds_dwordx4 v[126:127], off
	v_lshl_add_u64 v[126:127], v[116:117], 0, s[30:31]
	s_add_u32 m0, s39, 0x4000
	s_nop 0
	global_load_lds_dwordx4 v[126:127], off
	s_mov_b64 s[42:43], 0x100
	v_lshl_add_u64 v[124:125], v[124:125], 0, s[42:43]
	v_lshl_add_u64 v[122:123], v[122:123], 0, s[42:43]
	v_lshl_add_u64 v[120:121], v[120:121], 0, s[42:43]
	v_lshl_add_u64 v[236:237], v[118:119], 0, s[42:43]
	v_lshl_add_u64 v[126:127], v[116:117], 0, s[42:43]
	v_add_u32_e32 v170, v147, v128
	v_add_u32_e32 v172, v149, v148
	s_mov_b32 s35, 0
	s_mov_b32 s41, 42
	s_waitcnt vmcnt(15)
	s_barrier
	ds_read_b128 v[134:137], v170
	ds_read_b128 v[138:141], v170 offset:1024
	ds_read_b128 v[150:153], v170 offset:2048
	ds_read_b128 v[154:157], v170 offset:3072
	ds_read_b128 v[158:161], v170 offset:4096
	ds_read_b128 v[162:165], v170 offset:5120
	ds_read_b128 v[166:169], v172 offset:12288
	ds_read_b128 v[200:203], v172 offset:13312
	ds_read_b128 v[204:207], v172 offset:14336
	ds_read_b128 v[208:211], v172 offset:15360

.LBB0_127:
	s_ashr_i32 s0, s9, 31
	s_lshr_b32 s0, s0, 27
	s_add_i32 s1, s9, s0
	s_and_b32 s0, s1, 0x3ffffe0
	s_sub_i32 s0, s9, s0
	s_mulk_i32 s0, 0xc0
	s_lshl_b32 s1, s1, 2
	s_and_b32 s4, s1, 0xffffff80
	s_ashr_i32 s1, s0, 31
	s_lshl_b64 s[6:7], s[0:1], 11
	v_lshl_add_u64 v[0:1], v[98:99], 0, s[6:7]
	v_readfirstlane_b32 s1, v142
	s_ashr_i32 s5, s4, 31
	v_lshl_add_u64 v[4:5], v[0:1], 0, v[112:113]
	s_mov_b32 m0, s1
	v_readfirstlane_b32 s1, v143
	s_lshl_b64 s[12:13], s[4:5], 11
	global_load_lds_dwordx4 v[4:5], off
	v_lshl_add_u64 v[6:7], v[0:1], 0, v[114:115]
	s_mov_b32 m0, s1
	v_readfirstlane_b32 s1, v144
	v_add_u32_e32 v10, 0x3000, v142
	v_lshl_add_u64 v[2:3], v[100:101], 0, s[12:13]
	global_load_lds_dwordx4 v[6:7], off
	v_lshl_add_u64 v[0:1], v[0:1], 0, v[96:97]
	s_mov_b32 m0, s1
	v_readfirstlane_b32 s1, v10
	v_add_u32_e32 v10, 0x4000, v142
	global_load_lds_dwordx4 v[0:1], off
	v_lshl_add_u64 v[8:9], v[2:3], 0, v[112:113]
	s_mov_b32 m0, s1
	v_readfirstlane_b32 s1, v10
	v_add_u32_e32 v10, 0x5000, v142
	global_load_lds_dwordx4 v[8:9], off
	v_lshl_add_u64 v[2:3], v[2:3], 0, v[114:115]
	s_mov_b32 m0, s1
	v_readfirstlane_b32 s1, v10
	global_load_lds_dwordx4 v[2:3], off
	v_lshl_add_u64 v[4:5], v[4:5], 0, 64
	s_mov_b32 m0, s1
	v_lshl_add_u64 v[0:1], v[0:1], 0, 64
	global_load_lds_dwordx4 v[4:5], off
	v_lshl_add_u64 v[4:5], v[6:7], 0, 64
	v_add_u32_e32 v6, 0x6000, v142
	s_mov_b32 s10, 2
	v_readfirstlane_b32 s1, v6
	s_mov_b32 m0, s1
	v_lshl_add_u64 v[116:117], v[102:103], 0, s[12:13]
	global_load_lds_dwordx4 v[4:5], off
	v_add_u32_e32 v4, 0x7000, v142
	v_lshl_add_u64 v[118:119], v[104:105], 0, s[12:13]
	v_readfirstlane_b32 s1, v4
	v_add_u32_e32 v4, 0x8000, v142
	s_mov_b32 m0, s1
	v_readfirstlane_b32 s1, v4
	global_load_lds_dwordx4 v[0:1], off
	v_lshl_add_u64 v[0:1], v[8:9], 0, 64
	s_mov_b32 m0, s1
	v_lshl_add_u64 v[120:121], v[106:107], 0, s[6:7]
	global_load_lds_dwordx4 v[0:1], off
	v_lshl_add_u64 v[0:1], v[2:3], 0, 64
	v_add_u32_e32 v2, 0x9000, v142
	v_lshl_add_u64 v[122:123], v[108:109], 0, s[6:7]
	v_readfirstlane_b32 s1, v2
	s_mov_b32 m0, s1
	v_lshl_add_u64 v[124:125], v[110:111], 0, s[6:7]
	global_load_lds_dwordx4 v[0:1], off
	v_mov_b32_e32 v0, 0
	s_mov_b32 s1, 0
	s_mov_b64 s[6:7], 0
	v_mov_b32_e32 v1, v0
	v_mov_b32_e32 v2, v0
	v_mov_b32_e32 v3, v0
	v_mov_b32_e32 v12, v0
	v_mov_b32_e32 v13, v0
	v_mov_b32_e32 v14, v0
	v_mov_b32_e32 v15, v0
	v_mov_b32_e32 v4, v0
	v_mov_b32_e32 v5, v0
	v_mov_b32_e32 v6, v0
	v_mov_b32_e32 v7, v0
	v_mov_b32_e32 v8, v0
	v_mov_b32_e32 v9, v0
	v_mov_b32_e32 v10, v0
	v_mov_b32_e32 v11, v0
	v_mov_b32_e32 v16, v0
	v_mov_b32_e32 v17, v0
	v_mov_b32_e32 v18, v0
	v_mov_b32_e32 v19, v0
	v_mov_b32_e32 v20, v0
	v_mov_b32_e32 v21, v0
	v_mov_b32_e32 v22, v0
	v_mov_b32_e32 v23, v0
	v_mov_b32_e32 v24, v0
	v_mov_b32_e32 v25, v0
	v_mov_b32_e32 v26, v0
	v_mov_b32_e32 v27, v0
	v_mov_b32_e32 v28, v0
	v_mov_b32_e32 v29, v0
	v_mov_b32_e32 v30, v0
	v_mov_b32_e32 v31, v0
	v_mov_b32_e32 v32, v0
	v_mov_b32_e32 v33, v0
	v_mov_b32_e32 v34, v0
	v_mov_b32_e32 v35, v0
	v_mov_b32_e32 v36, v0
	v_mov_b32_e32 v37, v0
	v_mov_b32_e32 v38, v0
	v_mov_b32_e32 v39, v0
	v_mov_b32_e32 v40, v0
	v_mov_b32_e32 v41, v0
	v_mov_b32_e32 v42, v0
	v_mov_b32_e32 v43, v0
	v_mov_b32_e32 v44, v0
	v_mov_b32_e32 v45, v0
	v_mov_b32_e32 v46, v0
	v_mov_b32_e32 v47, v0
	v_mov_b32_e32 v48, v0
	v_mov_b32_e32 v49, v0
	v_mov_b32_e32 v50, v0
	v_mov_b32_e32 v51, v0
	v_mov_b32_e32 v52, v0
	v_mov_b32_e32 v53, v0
	v_mov_b32_e32 v54, v0
	v_mov_b32_e32 v55, v0
	v_mov_b32_e32 v56, v0
	v_mov_b32_e32 v57, v0
	v_mov_b32_e32 v58, v0
	v_mov_b32_e32 v59, v0
	v_mov_b32_e32 v60, v0
	v_mov_b32_e32 v61, v0
	v_mov_b32_e32 v62, v0
	v_mov_b32_e32 v63, v0
	v_mov_b32_e32 v64, v0
	v_mov_b32_e32 v65, v0
	v_mov_b32_e32 v66, v0
	v_mov_b32_e32 v67, v0
	v_mov_b32_e32 v68, v0
	v_mov_b32_e32 v69, v0
	v_mov_b32_e32 v70, v0
	v_mov_b32_e32 v71, v0
	v_mov_b32_e32 v72, v0
	v_mov_b32_e32 v73, v0
	v_mov_b32_e32 v74, v0
	v_mov_b32_e32 v75, v0
	v_mov_b32_e32 v76, v0
	v_mov_b32_e32 v77, v0
	v_mov_b32_e32 v78, v0
	v_mov_b32_e32 v79, v0
	v_mov_b32_e32 v80, v0
	v_mov_b32_e32 v81, v0
	v_mov_b32_e32 v82, v0
	v_mov_b32_e32 v83, v0
	v_mov_b32_e32 v84, v0
	v_mov_b32_e32 v85, v0
	v_mov_b32_e32 v86, v0
	v_mov_b32_e32 v87, v0
	v_mov_b32_e32 v88, v0
	v_mov_b32_e32 v89, v0
	v_mov_b32_e32 v90, v0
	v_mov_b32_e32 v91, v0
	v_mov_b32_e32 v92, v0
	v_mov_b32_e32 v93, v0
	v_mov_b32_e32 v94, v0
	v_mov_b32_e32 v95, v0
	v_readfirstlane_b32 s34, v142
	s_mov_b32 s36, 0x5000
	s_mov_b32 s37, 0xffff1000
	ds_read_b32 v252, v183
	ds_read_b32 v253, v184
	s_add_u32 s39, s34, 0xa000
	v_lshl_add_u64 v[126:127], v[124:125], 0, s[2:3]
	s_mov_b32 m0, s39
	s_nop 0
	global_load_lds_dwordx4 v[126:127], off
	v_lshl_add_u64 v[126:127], v[122:123], 0, s[2:3]
	s_add_u32 m0, s39, 0x1000
	s_nop 0
	global_load_lds_dwordx4 v[126:127], off
	v_lshl_add_u64 v[126:127], v[120:121], 0, s[2:3]
	s_add_u32 m0, s39, 0x2000
	s_nop 0
	global_load_lds_dwordx4 v[126:127], off
	v_lshl_add_u64 v[126:127], v[118:119], 0, s[2:3]
	s_add_u32 m0, s39, 0x3000
	s_nop 0
	global_load_lds_dwordx4 v[126:127], off
	v_lshl_add_u64 v[126:127], v[116:117], 0, s[2:3]
	s_add_u32 m0, s39, 0x4000
	s_nop 0
	global_load_lds_dwordx4 v[126:127], off
	s_waitcnt lgkmcnt(0)
	v_readfirstlane_b32 s46, v252
	v_readfirstlane_b32 s47, v253
	s_barrier
	s_add_u32 s39, s34, 0xf000
	v_lshl_add_u64 v[126:127], v[124:125], 0, s[30:31]
	s_mov_b32 m0, s39
	s_nop 0
	global_load_lds_dwordx4 v[126:127], off
	v_lshl_add_u64 v[126:127], v[122:123], 0, s[30:31]
	s_add_u32 m0, s39, 0x1000
	s_nop 0
	global_load_lds_dwordx4 v[126:127], off
	v_lshl_add_u64 v[126:127], v[120:121], 0, s[30:31]
	s_add_u32 m0, s39, 0x2000
	s_nop 0
	global_load_lds_dwordx4 v[126:127], off
	v_lshl_add_u64 v[126:127], v[118:119], 0, s[30:31]
	s_add_u32 m0, s39, 0x3000
	s_nop 0
	global_load_lds_dwordx4 v[126:127], off
	v_lshl_add_u64 v[126:127], v[116:117], 0, s[30:31]
	s_add_u32 m0, s39, 0x4000
	s_nop 0
	global_load_lds_dwordx4 v[126:127], off
	s_mov_b64 s[42:43], 0x100
	v_lshl_add_u64 v[124:125], v[124:125], 0, s[42:43]
	v_lshl_add_u64 v[122:123], v[122:123], 0, s[42:43]
	v_lshl_add_u64 v[120:121], v[120:121], 0, s[42:43]
	v_lshl_add_u64 v[236:237], v[118:119], 0, s[42:43]
	v_lshl_add_u64 v[126:127], v[116:117], 0, s[42:43]
	v_add_u32_e32 v170, v147, v128
	v_add_u32_e32 v172, v149, v148
	s_mov_b32 s35, 0
	s_mov_b32 s41, 14
	s_waitcnt vmcnt(15)
	s_barrier
	ds_read_b128 v[134:137], v170
	ds_read_b128 v[138:141], v170 offset:1024
	ds_read_b128 v[150:153], v170 offset:2048
	ds_read_b128 v[154:157], v170 offset:3072
	ds_read_b128 v[158:161], v170 offset:4096
	ds_read_b128 v[162:165], v170 offset:5120
	ds_read_b128 v[166:169], v172 offset:12288
	ds_read_b128 v[200:203], v172 offset:13312
	ds_read_b128 v[204:207], v172 offset:14336
	ds_read_b128 v[208:211], v172 offset:15360
